# phase 3 order mix: odd groups of 8 workgroups run their attention item before their scan item (others scan first), so scan and attention overlap chip-wide
# baseline (speedup 1.0000x reference)
; __global__ void __launch_bounds__(NTHREADS, 2) fwd_kernel(Params p) {
;     ...
;     if (RUN(3)) {
;         const int vcu = (G % 8 == 0) ? (cid & 7) * (G >> 3) + (cid >> 3) : cid;
;         if (p.flags & 1) for (int v = vcu; v < 256; v += G) { const int bh = v >> 3, g_ = (v >> 2) & 1, es_ = v & 3; scan_item(p, (g_ * 32 + bh) * 4 + es_, lds); }
.LBB0_290:
	s_mov_b32 s98, 0
	v_readlane_b32 s4, v246, 12
	s_cmp_lt_i32 s4, 4
	s_cselect_b64 s[66:67], -1, 0
	s_and_b64 s[0:1], s[66:67], s[0:1]
	s_andn2_b64 vcc, exec, s[0:1]
	v_readlane_b32 s5, v246, 13
	v_readlane_b32 s6, v246, 14
	v_readlane_b32 s7, v246, 15
	s_cbranch_vccnz .LBB0_466

; __device__ __forceinline__ void scan_item(const Params& p, int item, unsigned char* lds) {
;     const int tid = threadIdx.x, lane = tid & 63, w = tid >> 6, fr = lane & 15, fq = lane >> 4;
;     const int seq = item >> 2, es = item & 3, g = seq >> 5, b = (seq >> 2) & 7, h = seq & 3;
;     unsigned char* ws = p.ws; unsigned char* dout = (unsigned char*)p.out;
;     const bf16_t* Qc = (const bf16_t*)(ws + WS_QC); const bf16_t* Kc = (const bf16_t*)(ws + WS_KC);
;     const bf16_t* KcT = (const bf16_t*)(dout + DO_KCT); const bf16_t* VTml = (const bf16_t*)(dout + DO_VTML);
;     const float* Bv = (const float*)(ws + WS_BV); const float* Av = (const float*)(ws + WS_AV); const float* PMv = (const float*)(ws + WS_PMV);
;     const float* BL = (const float*)(ws + WS_BL); const float* AM = (const float*)(ws + WS_AM);
;     bf16_t* Hout = (bf16_t*)(ws + WS_HOUT);
;     unsigned short* Cs = (unsigned short*)lds;
;     float* mst = (float*)(lds + 43008); float* mnw = mst + 32; float* bls = mst + 64;
;     float* SC = (float*)(lds + 43520);
;     unsigned char* Ks = lds + 47104;
;     unsigned char* Vs = lds + 112640;
;     for (int i = tid; i < 80 * 264 / 2; i += NTHREADS) ((unsigned*)Cs)[i] = 0u;
;     if (tid == 0) { float m = -1.0e30f;
;         for (int c = 0; c < 32; ++c) { const float bl = BL[seq * 32 + c], am = AM[seq * 32 + c]; mst[c] = m; bls[c] = bl; const float mn = fmaxf(bl + m, bl + am); mnw[c] = mn; m = mn; } }
;     f32x4 stC[2][5];
; #pragma unroll
;     for (int dd = 0; dd < 2; ++dd)
; #pragma unroll
;         for (int et = 0; et < 5; ++et) stC[dd][et] = (f32x4){0.f, 0.f, 0.f, 0.f};
;     const u32x4 ones4 = (fr == 0) ? (u32x4){0x3f803f80u, 0x3f803f80u, 0x3f803f80u, 0x3f803f80u} : (u32x4){0u, 0u, 0u, 0u};
;     const bf16x8 onesf = __builtin_bit_cast(bf16x8, ones4);
;     const size_t seqoff = (size_t)seq * 4096;
;     const int ut = 16 * w + fr;
;     const int krow0 = tid >> 5, kch = tid & 31, vs0 = tid >> 3, vc16 = tid & 7;
;     const bf16_t* kU = Kc + (size_t)b * 4096 * 1024 + h * 256; const unsigned kl = krow0 * 1024 + kch * 8;
;     const bf16_t* vU = (const bf16_t*)(ws + WS_MLV) + (size_t)b * 4096 * 1024 + h * 256 + es * 64; const unsigned vl = vs0 * 1024 + vc16 * 8;
;     const float* sU = Av + seqoff; const int sl_ = (tid < 128 ? 0 : (tid < 256 ? 262144 : -262144)) + (tid & 127);
.LBB0_293:
	v_readlane_b32 s0, v246, 12
	v_readlane_b32 s2, v246, 14
	v_readlane_b32 s1, v246, 13
	s_bitcmp1_b32 s2, 0
	v_readlane_b32 s3, v246, 15
	s_cselect_b64 s[0:1], -1, 0
	s_cmpk_lt_i32 s38, 0x100
	s_cselect_b64 s[2:3], -1, 0
	v_writelane_b32 v246, s2, 41
	s_and_b64 s[0:1], s[0:1], s[2:3]
	s_andn2_b64 vcc, exec, s[0:1]
	v_writelane_b32 v246, s3, 42
	s_cbranch_vccnz .LBB0_315
	s_cmp_lg_u32 s98, 0
	s_cbranch_scc1 .Lsw_scan
	s_bitcmp1_b32 s38, 3
	s_cbranch_scc0 .Lsw_scan
	s_mov_b32 s98, 1
	s_branch .LBB0_315
.Lsw_scan:
	v_writelane_b32 v246, s66, 43
	v_and_b32_e32 v5, 15, v144
	v_lshrrev_b32_e32 v4, 4, v144
	v_writelane_b32 v246, s67, 44
	v_cmp_eq_u32_e32 vcc, 0, v5
	v_readlane_b32 s0, v246, 10
	v_readlane_b32 s1, v246, 11
	s_add_u32 s2, s0, 0x8800000
	v_writelane_b32 v246, s2, 45
	s_addc_u32 s2, s1, 0
	v_writelane_b32 v246, s2, 46
	s_add_u32 s2, s0, 0x8200000
	s_addc_u32 s3, s1, 0
	v_writelane_b32 v246, s2, 47
	v_mov_b32_e32 v0, 0x3f803f80
	s_waitcnt vmcnt(0)
	v_bfe_u32 v6, v144, 4, 2
	v_writelane_b32 v246, s3, 48
	s_add_u32 s2, s0, 0x8410000
	v_writelane_b32 v246, s2, 49
	s_addc_u32 s2, s1, 0
	v_writelane_b32 v246, s2, 50
	s_add_u32 s2, s0, 0xc800000
	v_writelane_b32 v246, s2, 51
	s_addc_u32 s2, s1, 0
	v_writelane_b32 v246, s2, 52
	s_add_u32 s2, s0, 0x1c800000
	v_writelane_b32 v246, s2, 53
	s_addc_u32 s2, s1, 0
	v_writelane_b32 v246, s2, 54
	s_add_u32 s2, s0, 0x8400000
	v_writelane_b32 v246, s2, 55
	s_addc_u32 s2, s1, 0
	v_writelane_b32 v246, s2, 56
	s_add_u32 s0, s0, 0x24800000
	v_writelane_b32 v246, s0, 57
	s_addc_u32 s0, s1, 0
	v_writelane_b32 v246, s0, 58
	s_movk_i32 s0, 0x100
	v_cndmask_b32_e32 v0, 0, v0, vcc
	v_cmp_gt_u32_e32 vcc, s0, v144
	v_mov_b32_e32 v8, 0xfffc0000
	v_mov_b32_e32 v9, 0x40000
	s_movk_i32 s0, 0x7f
	v_bitop3_b32 v4, v4, v5, 3 bitop3:0x6c
	v_lshrrev_b32_e32 v150, 5, v144
	v_and_b32_e32 v7, 31, v144
	v_cndmask_b32_e32 v8, v8, v9, vcc
	v_cmp_lt_u32_e32 vcc, s0, v144
	v_lshlrev_b32_e32 v166, 4, v4
	v_bitop3_b32 v4, v6, v5, 4 bitop3:0x36
	v_lshl_or_b32 v145, v159, 4, v5
	v_lshlrev_b32_e32 v152, 3, v7
	v_cndmask_b32_e32 v8, 0, v8, vcc
	v_bitop3_b32 v7, v150, v7, 15 bitop3:0x6c
	v_lshlrev_b32_e32 v167, 4, v4
	v_bitop3_b32 v4, v6, v5, 8 bitop3:0x36
	v_lshlrev_b32_e32 v9, 10, v145
	v_lshlrev_b32_e32 v153, 2, v6
	v_and_or_b32 v157, v144, s0, v8
	s_movk_i32 s0, 0x180
	v_lshlrev_b32_e32 v8, 9, v150
	v_lshlrev_b32_e32 v7, 4, v7
	v_lshl_add_u32 v162, v5, 9, 0
	v_lshlrev_b32_e32 v168, 4, v4
	v_bitop3_b32 v4, v6, v5, 12 bitop3:0x36
	v_or_b32_e32 v154, v9, v153
	v_lshl_or_b32 v158, v6, 3, v9
	v_cmp_gt_u32_e64 s[6:7], s0, v144
	v_add3_u32 v160, 0, v8, v7
	v_lshl_add_u32 v8, v5, 4, v162
	v_lshlrev_b32_e32 v9, 4, v6
	s_movk_i32 s0, 0xfdf2
	v_lshlrev_b32_e32 v169, 4, v4
	v_bitop3_b32 v4, v6, v5, 16 bitop3:0x36
	v_add_u32_e32 v164, v8, v9
	v_mad_i32_i24 v8, v5, s0, v8
	v_lshlrev_b32_e32 v170, 4, v4
	v_bitop3_b32 v4, v6, v5, 20 bitop3:0x36
	v_cmp_ge_u32_e64 s[0:1], v153, v145
	v_lshlrev_b32_e32 v171, 4, v4
	v_bitop3_b32 v4, v6, v5, 24 bitop3:0x36
	v_writelane_b32 v246, s0, 59
	v_lshlrev_b32_e32 v172, 4, v4
	v_bitop3_b32 v4, v6, v5, 28 bitop3:0x36
	v_writelane_b32 v246, s1, 60
	v_cmp_le_u32_e64 s[0:1], v153, v145
	v_lshlrev_b32_e32 v173, 4, v4
	v_or_b32_e32 v4, 1, v153
	v_writelane_b32 v246, s0, 61
	v_bfe_u32 v10, v144, 2, 2
	v_bfe_u32 v11, v144, 1, 1
	v_writelane_b32 v246, s1, 62
	v_cmp_ge_u32_e64 s[0:1], v4, v145
	v_or_b32_e32 v4, 2, v153
	v_lshl_or_b32 v11, v159, 2, v11
	v_writelane_b32 v246, s0, 63
	v_lshlrev_b32_e32 v12, 3, v144
	v_and_b32_e32 v12, 8, v12
	v_writelane_b32 v245, s1, 0
	v_cmp_lt_u32_e64 s[0:1], v153, v145
	v_mul_u32_u24_e32 v6, 0x420, v6
	v_bitop3_b32 v14, v153, v11, v10 bitop3:0x36
	v_writelane_b32 v245, s0, 1
	v_lshlrev_b32_e32 v6, 1, v6
	v_lshlrev_b32_e32 v14, 4, v14
	v_writelane_b32 v245, s1, 2
	v_cmp_ge_u32_e64 s[0:1], v4, v145
	v_and_b32_e32 v155, 7, v144
	v_mul_u32_u24_e32 v7, 0x210, v5
	v_writelane_b32 v245, s0, 3
	v_add_u32_e32 v9, 0, v9
	v_lshlrev_b32_e32 v165, 8, v5
	v_writelane_b32 v245, s1, 4
	v_cmp_le_u32_e64 s[0:1], v4, v145
	v_or_b32_e32 v4, 3, v153
	v_mov_b32_e32 v1, v0
	v_writelane_b32 v245, s0, 5
	s_waitcnt lgkmcnt(0)
	v_mov_b32_e32 v2, v0
	v_mov_b32_e32 v3, v0
	v_writelane_b32 v245, s1, 6
	v_cmp_ge_u32_e64 s[0:1], v4, v145
	v_lshrrev_b32_e32 v151, 3, v144
	v_lshlrev_b32_e32 v156, 3, v155
	v_writelane_b32 v245, s0, 7
	v_add_u32_e32 v161, 0xb800, v160
	v_add_u32_e32 v163, 0xb800, v162
	v_writelane_b32 v245, s1, 8
	v_cmp_le_u32_e64 s[0:1], v4, v145
	v_or_b32_e32 v4, 19, v153
	v_add_u32_e32 v183, 0xfffffe00, v144
	v_writelane_b32 v245, s0, 9
	v_lshl_add_u32 v184, v144, 2, 0
	v_mov_b32_e32 v135, 0
	v_writelane_b32 v245, s1, 10
	v_cmp_le_u32_e64 s[0:1], v4, v145
	s_add_i32 s42, 0, 0xa800
	v_add_u32_e32 v185, v9, v7
	v_writelane_b32 v245, s0, 11
	s_mov_b32 s35, s38
	s_nop 0
	v_writelane_b32 v245, s1, 12
	v_cmp_ge_u32_e64 s[0:1], v4, v145
	v_or_b32_e32 v4, 18, v153
	s_nop 0
	v_writelane_b32 v245, s0, 13
	s_nop 1
	v_writelane_b32 v245, s1, 14
	v_cmp_le_u32_e64 s[0:1], v4, v145
	s_nop 1
	v_writelane_b32 v245, s0, 15
	s_nop 1
	v_writelane_b32 v245, s1, 16
	v_cmp_ge_u32_e64 s[0:1], v4, v145
	v_or_b32_e32 v4, 17, v153
	s_nop 0
	v_writelane_b32 v245, s0, 17
	s_nop 1
	v_writelane_b32 v245, s1, 18
	v_cmp_le_u32_e64 s[0:1], v4, v145
	s_nop 1
	v_writelane_b32 v245, s0, 19
	s_nop 1
	v_writelane_b32 v245, s1, 20
	v_cmp_ge_u32_e64 s[0:1], v4, v145
	v_or_b32_e32 v4, 16, v153
	s_nop 0
	v_writelane_b32 v245, s0, 21
	s_nop 1
	v_writelane_b32 v245, s1, 22
	v_cmp_le_u32_e64 s[0:1], v4, v145
	s_nop 1
	v_writelane_b32 v245, s0, 23
	s_nop 1
	v_writelane_b32 v245, s1, 24
	v_cmp_ge_u32_e64 s[0:1], v4, v145
	v_or_b32_e32 v4, 32, v153
; #define LAS __attribute__((address_space(3)))
; __device__ __forceinline__ unsigned pk2(float lo, float hi) { unsigned r; asm("v_cvt_pk_bf16_f32 %0, %1, %2" : "=v"(r) : "v"(lo), "v"(hi)); return r; }
; __device__ __forceinline__ void scan_item(const Params& p, int item, unsigned char* lds) {
;     ...
;                     const int sp = st - 1; const f32x4 av_ = *(const f32x4*)(SCc + 16 * sp + 4 * fq);
; #pragma unroll
;                     for (int j = 0; j < 4; ++j) { const int us = 16 * sp + 4 * fq + j; const bool ok = g ? (us >= ut) : (us <= ut);
;                         const float dwv = ok ? __expf(av_[j] - M_t) : 0.f; sg[4 * (sp & 1) + j] = accp[j] * dwv; }
;                     if (sp & 1) { u32x4 wv; wv.x = pk2(sg[0], sg[1]); wv.y = pk2(sg[2], sg[3]); wv.z = pk2(sg[4], sg[5]); wv.w = pk2(sg[6], sg[7]); pf[sp >> 1] = __builtin_bit_cast(bf16x8, wv); }
;                 }
;                 accp = a;
;             }
;             const f32x4 av7 = *(const f32x4*)(SCc + 16 * 7 + 4 * fq);
; #pragma unroll
;             for (int j = 0; j < 4; ++j) { const int us = 16 * 7 + 4 * fq + j; const bool ok = g ? (us >= ut) : (us <= ut);
;                 const float dwv = ok ? __expf(av7[j] - M_t) : 0.f; sg[4 + j] = accp[j] * dwv; }
;     ...
;                 for (int hf = 0; hf < 2; ++hf) { const int row = 32 * k2 + 16 * hf + 4 * fq + (fr >> 2), ch = 4 * w + 2 * dd + ((fr & 3) >> 1);
;                     typedef short v4i16_t __attribute__((ext_vector_type(4)));
;                     const v4i16_t tv = __builtin_amdgcn_ds_read_tr16_b64_v4i16((LAS v4i16_t*)(LAS unsigned char*)(Ks + row * 512 + ((ch ^ (row & 15)) << 4) + 8 * (fr & 1)));
	s_nop 0
	v_writelane_b32 v245, s0, 25
	s_nop 1
	v_writelane_b32 v245, s1, 26
	v_cmp_ge_u32_e64 s[0:1], v4, v145
	s_nop 1
	v_writelane_b32 v245, s0, 27
	s_nop 1
	v_writelane_b32 v245, s1, 28
	v_cmp_le_u32_e64 s[0:1], v4, v145
	v_or_b32_e32 v4, 33, v153
	s_nop 0
	v_writelane_b32 v245, s0, 29
	s_nop 1
	v_writelane_b32 v245, s1, 30
	v_cmp_ge_u32_e64 s[0:1], v4, v145
	s_nop 1
	v_writelane_b32 v245, s0, 31
	s_nop 1
	v_writelane_b32 v245, s1, 32
	v_cmp_le_u32_e64 s[0:1], v4, v145
	v_or_b32_e32 v4, 34, v153
	s_nop 0
	v_writelane_b32 v245, s0, 33
	s_nop 1
	v_writelane_b32 v245, s1, 34
	v_cmp_ge_u32_e64 s[0:1], v4, v145
	s_nop 1
	v_writelane_b32 v245, s0, 35
	s_nop 1
	v_writelane_b32 v245, s1, 36
	v_cmp_le_u32_e64 s[0:1], v4, v145
	v_or_b32_e32 v4, 35, v153
	s_nop 0
	v_writelane_b32 v245, s0, 37
	s_nop 1
	v_writelane_b32 v245, s1, 38
	v_cmp_ge_u32_e64 s[0:1], v4, v145
	s_nop 1
	v_writelane_b32 v245, s0, 39
	s_nop 1
	v_writelane_b32 v245, s1, 40
	v_cmp_le_u32_e64 s[0:1], v4, v145
	v_or_b32_e32 v4, 51, v153
	s_nop 0
	v_writelane_b32 v245, s0, 41
	s_nop 1
	v_writelane_b32 v245, s1, 42
	v_cmp_le_u32_e64 s[0:1], v4, v145
	s_nop 1
	v_writelane_b32 v245, s0, 43
	s_nop 1
	v_writelane_b32 v245, s1, 44
	v_cmp_ge_u32_e64 s[0:1], v4, v145
	v_or_b32_e32 v4, 50, v153
	s_nop 0
	v_writelane_b32 v245, s0, 45
	s_nop 1
	v_writelane_b32 v245, s1, 46
	v_cmp_le_u32_e64 s[0:1], v4, v145
	s_nop 1
	v_writelane_b32 v245, s0, 47
	s_nop 1
	v_writelane_b32 v245, s1, 48
	v_cmp_ge_u32_e64 s[0:1], v4, v145
	v_or_b32_e32 v4, 49, v153
	s_nop 0
	v_writelane_b32 v245, s0, 49
	s_nop 1
	v_writelane_b32 v245, s1, 50
	v_cmp_le_u32_e64 s[0:1], v4, v145
	s_nop 1
	v_writelane_b32 v245, s0, 51
	s_nop 1
	v_writelane_b32 v245, s1, 52
	v_cmp_ge_u32_e64 s[0:1], v4, v145
	v_or_b32_e32 v4, 48, v153
	s_nop 0
	v_writelane_b32 v245, s0, 53
	s_nop 1
	v_writelane_b32 v245, s1, 54
	v_cmp_le_u32_e64 s[0:1], v4, v145
	s_nop 1
	v_writelane_b32 v245, s0, 55
	s_nop 1
	v_writelane_b32 v245, s1, 56
	v_cmp_ge_u32_e64 s[0:1], v4, v145
	v_or_b32_e32 v4, 64, v153
	s_nop 0
	v_writelane_b32 v245, s0, 57
	s_nop 1
	v_writelane_b32 v245, s1, 58
	v_cmp_ge_u32_e64 s[0:1], v4, v145
	s_nop 1
	v_writelane_b32 v245, s0, 59
	s_nop 1
	v_writelane_b32 v245, s1, 60
	v_cmp_le_u32_e64 s[0:1], v4, v145
	v_or_b32_e32 v4, 0x41, v153
	s_nop 0
	v_writelane_b32 v245, s0, 61
	s_nop 1
	v_writelane_b32 v245, s1, 62
	v_cmp_ge_u32_e64 s[0:1], v4, v145
	s_nop 1
	v_writelane_b32 v245, s0, 63
	s_nop 1
	v_writelane_b32 v244, s1, 0
	v_cmp_le_u32_e64 s[0:1], v4, v145
	v_or_b32_e32 v4, 0x42, v153
	s_nop 0
	v_writelane_b32 v244, s0, 1
	s_nop 1
	v_writelane_b32 v244, s1, 2
	v_cmp_ge_u32_e64 s[0:1], v4, v145
	s_nop 1
	v_writelane_b32 v244, s0, 3
	s_nop 1
	v_writelane_b32 v244, s1, 4
	v_cmp_le_u32_e64 s[0:1], v4, v145
	v_or_b32_e32 v4, 0x43, v153
	s_nop 0
	v_writelane_b32 v244, s0, 5
	s_nop 1
	v_writelane_b32 v244, s1, 6
	v_cmp_ge_u32_e64 s[0:1], v4, v145
	s_nop 1
	v_writelane_b32 v244, s0, 7
	s_nop 1
	v_writelane_b32 v244, s1, 8
	v_cmp_le_u32_e64 s[0:1], v4, v145
	v_or_b32_e32 v4, 0x53, v153
	s_nop 0
	v_writelane_b32 v244, s0, 9
	s_nop 1
	v_writelane_b32 v244, s1, 10
	v_cmp_le_u32_e64 s[0:1], v4, v145
	s_nop 1
	v_writelane_b32 v244, s0, 11
	s_nop 1
	v_writelane_b32 v244, s1, 12
	v_cmp_ge_u32_e64 s[0:1], v4, v145
	v_or_b32_e32 v4, 0x52, v153
	s_nop 0
	v_writelane_b32 v244, s0, 13
	s_nop 1
	v_writelane_b32 v244, s1, 14
	v_cmp_le_u32_e64 s[0:1], v4, v145
	s_nop 1
	v_writelane_b32 v244, s0, 15
	s_nop 1
	v_writelane_b32 v244, s1, 16
	v_cmp_ge_u32_e64 s[0:1], v4, v145
	v_or_b32_e32 v4, 0x51, v153
	s_nop 0
	v_writelane_b32 v244, s0, 17
	s_nop 1
	v_writelane_b32 v244, s1, 18
	v_cmp_le_u32_e64 s[0:1], v4, v145
	s_nop 1
	v_writelane_b32 v244, s0, 19
	s_nop 1
	v_writelane_b32 v244, s1, 20
	v_cmp_ge_u32_e64 s[0:1], v4, v145
	v_or_b32_e32 v4, 0x50, v153
	s_nop 0
	v_writelane_b32 v244, s0, 21
	s_nop 1
	v_writelane_b32 v244, s1, 22
	v_cmp_le_u32_e64 s[0:1], v4, v145
	s_nop 1
	v_writelane_b32 v244, s0, 23
	s_nop 1
	v_writelane_b32 v244, s1, 24
	v_cmp_ge_u32_e64 s[0:1], v4, v145
	v_or_b32_e32 v4, 0x63, v153
	s_nop 0
	v_writelane_b32 v244, s0, 25
	s_nop 1
	v_writelane_b32 v244, s1, 26
	v_cmp_le_u32_e64 s[0:1], v4, v145
	s_nop 1
	v_writelane_b32 v244, s0, 27
	s_nop 1
	v_writelane_b32 v244, s1, 28
	v_cmp_ge_u32_e64 s[0:1], v4, v145
	v_or_b32_e32 v4, 0x60, v153
	s_nop 0
	v_writelane_b32 v244, s0, 29
	s_nop 1
	v_writelane_b32 v244, s1, 30
	v_cmp_le_u32_e64 s[0:1], v4, v145
	s_nop 1
	v_writelane_b32 v244, s0, 31
	s_nop 1
	v_writelane_b32 v244, s1, 32
	v_cmp_ge_u32_e64 s[0:1], v4, v145
	v_or_b32_e32 v4, 0x61, v153
	s_nop 0
	v_writelane_b32 v244, s0, 33
	s_nop 1
	v_writelane_b32 v244, s1, 34
	v_cmp_le_u32_e64 s[0:1], v4, v145
	s_nop 1
	v_writelane_b32 v244, s0, 35
	s_nop 1
	v_writelane_b32 v244, s1, 36
	v_cmp_ge_u32_e64 s[0:1], v4, v145
	v_or_b32_e32 v4, 0x62, v153
	s_nop 0
	v_writelane_b32 v244, s0, 37
	s_nop 1
	v_writelane_b32 v244, s1, 38
	v_cmp_le_u32_e64 s[0:1], v4, v145
	s_nop 1
	v_writelane_b32 v244, s0, 39
	s_nop 1
	v_writelane_b32 v244, s1, 40
	v_cmp_ge_u32_e64 s[0:1], v4, v145
	v_or_b32_e32 v4, 0x70, v153
	s_nop 0
	v_writelane_b32 v244, s0, 41
	s_nop 1
	v_writelane_b32 v244, s1, 42
	v_cmp_ge_u32_e64 s[0:1], v4, v145
	s_nop 1
	v_writelane_b32 v244, s0, 43
	s_nop 1
	v_writelane_b32 v244, s1, 44
	v_cmp_le_u32_e64 s[0:1], v4, v145
	v_or_b32_e32 v4, 0x71, v153
	s_nop 0
	v_writelane_b32 v244, s0, 45
	s_nop 1
	v_writelane_b32 v244, s1, 46
	v_cmp_ge_u32_e64 s[0:1], v4, v145
	s_nop 1
	v_writelane_b32 v244, s0, 47
	s_nop 1
	v_writelane_b32 v244, s1, 48
	v_cmp_le_u32_e64 s[0:1], v4, v145
	v_or_b32_e32 v4, 0x72, v153
	s_nop 0
	v_writelane_b32 v244, s0, 49
	s_nop 1
	v_writelane_b32 v244, s1, 50
	v_cmp_ge_u32_e64 s[0:1], v4, v145
	s_nop 1
	v_writelane_b32 v244, s0, 51
	s_nop 1
	v_writelane_b32 v244, s1, 52
	v_cmp_le_u32_e64 s[0:1], v4, v145
	v_or_b32_e32 v4, 0x73, v153
	s_nop 0
	v_writelane_b32 v244, s0, 53
	s_nop 1
	v_writelane_b32 v244, s1, 54
	v_cmp_ge_u32_e64 s[0:1], v4, v145
	s_nop 1
	v_writelane_b32 v244, s0, 55
	s_nop 1
	v_writelane_b32 v244, s1, 56
	v_cmp_le_u32_e64 s[0:1], v4, v145
	v_or_b32_e32 v4, v153, v10
	v_lshlrev_b32_e32 v4, 9, v4
	v_or_b32_e32 v174, 0xc000, v4
	v_add_u32_e32 v13, 0, v4
	v_or_b32_e32 v175, 0x4000, v4
	v_or_b32_e32 v177, 0x8000, v4
	v_or_b32_e32 v4, 2, v11
	v_writelane_b32 v244, s0, 57
	v_bitop3_b32 v4, v153, v4, v10 bitop3:0x36
	v_lshlrev_b32_e32 v4, 4, v4
	v_writelane_b32 v244, s1, 58
	s_add_i32 s0, 0, 0xd800
	s_add_i32 s1, 0, 0xb800
	v_add_u32_e32 v10, v13, v4
	v_add3_u32 v179, s0, v4, v12
	v_add3_u32 v180, s1, v4, v12
	v_and_b32_e32 v4, 0x3c0, v144
	v_add3_u32 v181, v8, v4, v6
	v_add_u32_e32 v6, 0, v6
	v_lshlrev_b32_e32 v8, 1, v5
	v_add3_u32 v182, v6, v4, v8
	v_mbcnt_lo_u32_b32 v6, -1, 0
	v_mbcnt_hi_u32_b32 v6, -1, v6
	v_add_u32_e32 v15, v13, v14
	v_and_or_b32 v5, v6, 64, v5
	v_add3_u32 v176, s0, v14, v12
	v_add3_u32 v178, s1, v14, v12
	v_mov_b32_e32 v4, 0xf149f2ca
	v_add_u32_e32 v186, v15, v12
	v_add_u32_e32 v187, v10, v12
	v_lshlrev_b32_e32 v188, 2, v5
	s_branch .LBB0_296

; __global__ void __launch_bounds__(NTHREADS, 2) fwd_kernel(Params p) {
;     ...
;         if (p.flags & 2) {
;             float* rpl = (float*)lds;
;             for (int i = threadIdx.x; i < 16 * 15 * 31; i += NTHREADS) rpl[i] = p.in[2][i];
.LBB0_315:
	s_cmp_eq_u32 s98, 2
	s_cbranch_scc1 .Lsw_done
	v_readlane_b32 s0, v246, 12
	v_readlane_b32 s2, v246, 14
	s_bitcmp0_b32 s2, 1
	v_readlane_b32 s1, v246, 13
	v_readlane_b32 s3, v246, 15
	s_cbranch_scc1 .LBB0_466
	v_lshlrev_b32_e32 v4, 2, v144
	s_waitcnt vmcnt(0)
	v_mov_b32_e32 v5, 0
	s_waitcnt lgkmcnt(0)
	v_add_u32_e32 v2, 0xfffffe00, v144
	v_lshl_add_u64 v[0:1], s[20:21], 0, v[4:5]
	v_add_u32_e32 v3, 0, v4
	s_mov_b64 s[0:1], 0
	s_mov_b64 s[2:3], 0x800
	s_movk_i32 s4, 0x1b0f

; #define SEAM(k) do { if (RUN(k) && RUN((k) + 1)) { if ((k) == 0) cg::this_grid().sync(); else xcd_barrier(xbar); } } while (0)
; __global__ void __launch_bounds__(NTHREADS, 2) fwd_kernel(Params p) {
;     ...
;             for (int wgi = vcu; wgi < 256; wgi += G) na_wg_item(p, wgi, lds, rpl);
;         }
;     }
;     SEAM(3);
.LBB0_466:
	s_cmp_eq_u32 s98, 1
	s_cbranch_scc0 .Lsw_done
	s_mov_b32 s98, 2
	s_waitcnt vmcnt(0) lgkmcnt(0)
	s_barrier
	s_branch .Lsw_redo

; __global__ void __launch_bounds__(NTHREADS, 2) fwd_kernel(Params p) {
	.amdhsa_kernel _Z10fwd_kernel6Params
		.amdhsa_group_segment_fixed_size 0
		.amdhsa_private_segment_fixed_size 0
		.amdhsa_kernarg_size 440
		.amdhsa_user_sgpr_count 2
		.amdhsa_user_sgpr_dispatch_ptr 0
		.amdhsa_user_sgpr_queue_ptr 0
		.amdhsa_user_sgpr_kernarg_segment_ptr 1
		.amdhsa_user_sgpr_dispatch_id 0
		.amdhsa_user_sgpr_kernarg_preload_length 0
		.amdhsa_user_sgpr_kernarg_preload_offset 0
		.amdhsa_user_sgpr_private_segment_size 0
		.amdhsa_uses_dynamic_stack 0
		.amdhsa_enable_private_segment 0
		.amdhsa_system_sgpr_workgroup_id_x 1
		.amdhsa_system_sgpr_workgroup_id_y 0
		.amdhsa_system_sgpr_workgroup_id_z 0
		.amdhsa_system_sgpr_workgroup_info 0
		.amdhsa_system_vgpr_workitem_id 2
		.amdhsa_next_free_vgpr 247
		.amdhsa_next_free_sgpr 102
		.amdhsa_accum_offset 248
		.amdhsa_reserve_vcc 1
		.amdhsa_float_round_mode_32 0
		.amdhsa_float_round_mode_16_64 0
		.amdhsa_float_denorm_mode_32 3
		.amdhsa_float_denorm_mode_16_64 3
		.amdhsa_dx10_clamp 1
		.amdhsa_ieee_mode 1
		.amdhsa_fp16_overflow 0
		.amdhsa_tg_split 0
		.amdhsa_exception_fp_ieee_invalid_op 0
		.amdhsa_exception_fp_denorm_src 0
		.amdhsa_exception_fp_ieee_div_zero 0
		.amdhsa_exception_fp_ieee_overflow 0
		.amdhsa_exception_fp_ieee_underflow 0
		.amdhsa_exception_fp_ieee_inexact 0
		.amdhsa_exception_int_div_zero 0
	.end_amdhsa_kernel

; __global__ void __launch_bounds__(NTHREADS, 2) fwd_kernel(Params p) {
amdhsa.kernels:
  - .agpr_count:     0
    .args:
      - .offset:         0
        .size:           184
        .value_kind:     by_value
      - .offset:         184
        .size:           4
        .value_kind:     hidden_block_count_x
      - .offset:         188
        .size:           4
        .value_kind:     hidden_block_count_y
      - .offset:         192
        .size:           4
        .value_kind:     hidden_block_count_z
      - .offset:         196
        .size:           2
        .value_kind:     hidden_group_size_x
      - .offset:         198
        .size:           2
        .value_kind:     hidden_group_size_y
      - .offset:         200
        .size:           2
        .value_kind:     hidden_group_size_z
      - .offset:         202
        .size:           2
        .value_kind:     hidden_remainder_x
      - .offset:         204
        .size:           2
        .value_kind:     hidden_remainder_y
      - .offset:         206
        .size:           2
        .value_kind:     hidden_remainder_z
      - .offset:         224
        .size:           8
        .value_kind:     hidden_global_offset_x
      - .offset:         232
        .size:           8
        .value_kind:     hidden_global_offset_y
      - .offset:         240
        .size:           8
        .value_kind:     hidden_global_offset_z
      - .offset:         248
        .size:           2
        .value_kind:     hidden_grid_dims
      - .offset:         272
        .size:           8
        .value_kind:     hidden_multigrid_sync_arg
      - .offset:         304
        .size:           4
        .value_kind:     hidden_dynamic_lds_size
    .group_segment_fixed_size: 0
    .kernarg_segment_align: 8
    .kernarg_segment_size: 440
    .language:       OpenCL C
    .language_version:
      - 2
      - 0
    .max_flat_workgroup_size: 512
    .name:           _Z10fwd_kernel6Params
    .private_segment_fixed_size: 0
    .sgpr_count:     108
    .sgpr_spill_count: 189
    .symbol:         _Z10fwd_kernel6Params.kd
    .uniform_work_group_size: 1
    .uses_dynamic_stack: false
    .vgpr_count:     247
    .vgpr_spill_count: 0
    .wavefront_size: 64
